# v37 plus: chain items (GLA/LRU) use a workgroup-scope fence (vmcnt wait + barrier) before their in-workgroup combine instead of agent-scope L2 writeback+invalidate
# speedup vs baseline: 1.0098x; 1.0034x over previous
; DI void lru_combine(const Params& p, int seq, int npair, int tid_) {
;   int tid = tid_;
;   asm volatile("" : "+v"(tid));
;   const int sub = tid & 7, trow = tid >> 3;
;   const unsigned c0 = npair * 64 + sub * 8;
;   const u16* z = (const u16*)(p.ws + OFF_Z) + (size_t)seq * 2048 * 1760;
;   u16* mx = (u16*)(p.ws + OFF_H) + (size_t)seq * 2048 * 1024;
; DI void run_phase(const Params& p, int ph, char* smem, int* s_item, const XcdBarrier* xbp) {
;     ...
;           lru_wave(p, l, a >> 1, 4 * (a & 1) + (wv >> 1), wv & 1, smem + wv * 13312, tid & 63);
;           __threadfence();
;           __syncthreads();
;           lru_combine(p, a >> 1, 2 * (a & 1) + half, tl);
.LBB0_644:
	v_mov_b32_e32 v0, v192
	s_waitcnt vmcnt(0)
	s_barrier
	s_lshl_b32 s1, s97, 6
	v_ashrrev_i32_e32 v1, 3, v0
	v_lshlrev_b32_e32 v0, 3, v0
	v_and_b32_e32 v112, 56, v0
	s_add_i32 s1, s1, s5
	v_mul_lo_u32 v0, v1, s77
	v_lshl_add_u32 v113, v1, 10, s1
	v_add_u32_e32 v114, s1, v0
	s_mov_b32 s2, -8
	s_movk_i32 s5, 0x600
	s_mov_b64 s[30:31], s[34:35]

; DI void gla_combine(const Params& p, int l, int seq, int hp, int tid_) {
;   int tid = tid_;
;   asm volatile("" : "+v"(tid));
;   const int sub = tid & 7, rloc = tid >> 3;
;   const u16* z = (const u16*)(p.ws + OFF_Z) + (size_t)seq * 2048 * 1760;
;   u16* mx = (u16*)(p.ws + OFF_H) + (size_t)seq * 2048 * 1024;
;   const u16* gt = (const u16*)(p.ws + OFF_GT) + (size_t)seq * 2048 * 256;
;   const float* gop = p.in[26] + l * 64 + sub * 8;
;   float go[8];
; #pragma unroll
;   for (int e = 0; e < 8; e++) go[e] = gop[e];
; DI void run_phase(const Params& p, int ph, char* smem, int* s_item, const XcdBarrier* xbp) {
;     ...
;           gla_wave(p, l, it, wv >> 1, wv & 1, smem + wv * 13312, tid & 63);
;           __threadfence();
;           __syncthreads();
;           gla_combine(p, l, it, half, tl);
.LBB0_660:
	v_mov_b32_e32 v8, v192
	s_waitcnt vmcnt(0)
	s_barrier
	s_add_u32 s40, s90, s28
	v_lshlrev_b32_e32 v0, 3, v8
	v_and_b32_e32 v9, 56, v0
	v_lshlrev_b32_e32 v4, 2, v9
	global_load_dwordx4 v[0:3], v4, s[92:93] offset:16
	s_nop 0
	global_load_dwordx4 v[4:7], v4, s[92:93]
	v_ashrrev_i32_e32 v105, 3, v8
	v_lshlrev_b32_e32 v8, 6, v105
	s_addc_u32 s41, s91, s29
	s_lshl_b32 s1, s97, 7
	v_and_b32_e32 v8, 64, v8
	v_or3_b32 v132, v8, s1, v9
	v_xor_b32_e32 v8, 1, v130
	v_cmp_lt_i32_e32 vcc, v8, v124
	v_add_u32_e32 v133, 0x300, v132
	v_add_u32_e32 v104, 0x5e0, v132
	v_cndmask_b32_e32 v8, v130, v8, vcc
	v_lshlrev_b32_e32 v134, 2, v8
	v_xor_b32_e32 v8, 2, v130
	v_cmp_lt_i32_e32 vcc, v8, v124
	v_lshlrev_b32_e32 v137, 9, v105
	s_mov_b32 s2, -8
	v_cndmask_b32_e32 v8, v130, v8, vcc
	v_lshlrev_b32_e32 v135, 2, v8
	v_xor_b32_e32 v8, 4, v130
	v_cmp_lt_i32_e32 vcc, v8, v124
	s_movk_i32 s5, 0x600
	s_mov_b32 s8, 0x3c800000
	v_cndmask_b32_e32 v8, v130, v8, vcc
	v_lshlrev_b32_e32 v136, 2, v8
	s_mov_b32 s10, 0x358637bd
